# GEMM k-loop: next-tile DMA address/dest math rotated into the tail of the previous iteration (MFMA shadow) plus preheader copy; B base moved to v251
# speedup vs baseline: 1.1336x; 1.0016x over previous
; __device__ __forceinline__ void lds_barrier() { asm volatile("s_waitcnt lgkmcnt(0)\n\ts_barrier" ::: "memory"); }
; template <int EPI>
; __device__ void gemm_phase(const u16* __restrict__ A, const u16* __restrict__ Bt, void* __restrict__ Cv,
;                            int N, int K, int ldc, unsigned char* ldsraw, int G) {
;     ...
; #pragma unroll
;     for (int i = 0; i < 4; ++i)
; #pragma unroll
;       for (int j = 0; j < 4; ++j) acc[i][j] = (f32x4){0.f, 0.f, 0.f, 0.f};
;     ...
;     for (int kt = 0; kt < nk; ++kt) {
;       asm volatile("s_waitcnt vmcnt(6)" ::: "memory");
;       lds_barrier();
;       const int st2 = (st >= 1) ? st - 1 : 2;
;       GLDS(st2, kt + 2);
;       const u16* Asx = As + st * STG;
;       const u16* Bsx = Asx + GBM * GLD;
; #pragma unroll
;       for (int ks = 0; ks < 2; ++ks) {
;         const int fsw = ((ks * 4 + g4) ^ fx) * 8;
;         bf16x8 bfr[4];
; #pragma unroll
;         for (int jx = 0; jx < 4; ++jx) bfr[jx] = *(const bf16x8*)(Bsx + (wn * 64 + jx * 16 + l15) * GLD + fsw);
; #pragma unroll
;         for (int ix = 0; ix < 4; ++ix) {
;           const bf16x8 af = *(const bf16x8*)(Asx + (wm * 64 + ix * 16 + l15) * GLD + fsw);
.LBB0_19:
	v_mov_b32_e32 v2, 0
	s_mov_b32 s5, 0
	s_mov_b32 s6, 0
	v_mov_b32_e32 v3, v2
	v_mov_b32_e32 v4, v2
	v_mov_b32_e32 v5, v2
	v_mov_b32_e32 v8, v2
	v_mov_b32_e32 v9, v2
	v_mov_b32_e32 v10, v2
	v_mov_b32_e32 v11, v2
	v_mov_b32_e32 v12, v2
	v_mov_b32_e32 v13, v2
	v_mov_b32_e32 v14, v2
	v_mov_b32_e32 v15, v2
	v_mov_b32_e32 v16, v2
	v_mov_b32_e32 v17, v2
	v_mov_b32_e32 v18, v2
	v_mov_b32_e32 v19, v2
	v_mov_b32_e32 v20, v2
	v_mov_b32_e32 v21, v2
	v_mov_b32_e32 v22, v2
	v_mov_b32_e32 v23, v2
	v_mov_b32_e32 v24, v2
	v_mov_b32_e32 v25, v2
	v_mov_b32_e32 v26, v2
	v_mov_b32_e32 v27, v2
	v_mov_b32_e32 v28, v2
	v_mov_b32_e32 v29, v2
	v_mov_b32_e32 v30, v2
	v_mov_b32_e32 v31, v2
	v_mov_b32_e32 v32, v2
	v_mov_b32_e32 v33, v2
	v_mov_b32_e32 v34, v2
	v_mov_b32_e32 v35, v2
	v_mov_b32_e32 v36, v2
	v_mov_b32_e32 v37, v2
	v_mov_b32_e32 v38, v2
	v_mov_b32_e32 v39, v2
	v_mov_b32_e32 v40, v2
	v_mov_b32_e32 v41, v2
	v_mov_b32_e32 v42, v2
	v_mov_b32_e32 v43, v2
	v_mov_b32_e32 v44, v2
	v_mov_b32_e32 v45, v2
	v_mov_b32_e32 v46, v2
	v_mov_b32_e32 v47, v2
	v_mov_b32_e32 v48, v2
	v_mov_b32_e32 v49, v2
	v_mov_b32_e32 v50, v2
	v_mov_b32_e32 v51, v2
	v_mov_b32_e32 v52, v2
	v_mov_b32_e32 v53, v2
	v_mov_b32_e32 v54, v2
	v_mov_b32_e32 v55, v2
	v_mov_b32_e32 v56, v2
	v_mov_b32_e32 v57, v2
	v_mov_b32_e32 v58, v2
	s_waitcnt vmcnt(0)
	v_mov_b32_e32 v59, v2
	v_mov_b32_e32 v60, v2
	v_mov_b32_e32 v61, v2
	v_mov_b32_e32 v62, v2
	v_mov_b32_e32 v63, v2
	v_mov_b32_e32 v64, v2
	v_mov_b32_e32 v65, v2
	v_mov_b32_e32 v66, v2
	v_mov_b32_e32 v67, v2
	s_mul_i32 s8, s5, 0xc000
	s_min_u32 s7, s6, 61
	s_add_i32 s9, s8, 0xffff4000
	s_cmp_gt_i32 s5, 0
	s_cselect_b32 s9, s9, 0x18000
	s_lshl_b32 s98, s7, 7
	s_add_i32 s98, s98, 0x100
	s_add_i32 s7, s8, 0x100
	s_add_i32 s8, s9, s4
	s_add_i32 s9, s8, 0x2000
	s_add_i32 s11, s8, 0x4000
	s_add_i32 s12, s8, 0x6000
	s_add_i32 s13, s8, 0x8000
	s_add_i32 s14, s8, 0xa000
	v_lshl_add_u64 v[236:237], v[76:77], 0, s[98:99]
	v_lshl_add_u64 v[238:239], v[80:81], 0, s[98:99]
	v_lshl_add_u64 v[240:241], v[82:83], 0, s[98:99]
	v_lshl_add_u64 v[242:243], v[84:85], 0, s[98:99]
	v_lshl_add_u64 v[244:245], v[78:79], 0, s[98:99]
	v_lshl_add_u64 v[246:247], v[86:87], 0, s[98:99]
	v_lshl_add_u32 v109, v104, 1, s7
	v_add3_u32 v251, v109, v105, v106
	v_add3_u32 v109, v109, v107, v106
; __device__ __forceinline__ void lds_barrier() { asm volatile("s_waitcnt lgkmcnt(0)\n\ts_barrier" ::: "memory"); }
; template <int EPI>
; __device__ void gemm_phase(const u16* __restrict__ A, const u16* __restrict__ Bt, void* __restrict__ Cv,
;                            int N, int K, int ldc, unsigned char* ldsraw, int G) {
;     ...
;     for (int kt = 0; kt < nk; ++kt) {
;       asm volatile("s_waitcnt vmcnt(6)" ::: "memory");
;       lds_barrier();
;       const int st2 = (st >= 1) ? st - 1 : 2;
;       GLDS(st2, kt + 2);
;       const u16* Asx = As + st * STG;
;       const u16* Bsx = Asx + GBM * GLD;
; #pragma unroll
;       for (int ks = 0; ks < 2; ++ks) {
;         const int fsw = ((ks * 4 + g4) ^ fx) * 8;
;         bf16x8 bfr[4];
; #pragma unroll
;         for (int jx = 0; jx < 4; ++jx) bfr[jx] = *(const bf16x8*)(Bsx + (wn * 64 + jx * 16 + l15) * GLD + fsw);
; #pragma unroll
;         for (int ix = 0; ix < 4; ++ix) {
;           const bf16x8 af = *(const bf16x8*)(Asx + (wm * 64 + ix * 16 + l15) * GLD + fsw);
; #pragma unroll
;           for (int jx = 0; jx < 4; ++jx)
;             acc[ix][jx] = __builtin_amdgcn_mfma_f32_16x16x32_bf16(af, bfr[jx], acc[ix][jx], 0, 0, 0);
;         }
;       }
;       st = (st == 2) ? 0 : st + 1;
;     }
.LBB0_20:
	s_waitcnt vmcnt(6)
	s_waitcnt lgkmcnt(0)
	s_barrier
	s_mov_b32 s15, m0
	ds_read_b128 v[110:113], v109
	ds_read_b128 v[114:117], v251 offset:32768
	ds_read_b128 v[118:121], v251 offset:34816
	ds_read_b128 v[122:125], v109 offset:2048
	ds_read_b128 v[126:129], v251 offset:36864
	ds_read_b128 v[130:133], v251 offset:38912
	s_waitcnt lgkmcnt(4)
	v_mfma_f32_16x16x32_bf16 v[64:67], v[110:113], v[114:117], v[64:67]
	s_waitcnt lgkmcnt(3)
	v_mfma_f32_16x16x32_bf16 v[60:63], v[110:113], v[118:121], v[60:63]
	s_waitcnt lgkmcnt(1)
	v_mfma_f32_16x16x32_bf16 v[56:59], v[110:113], v[126:129], v[56:59]
	s_waitcnt lgkmcnt(0)
	s_mov_b32 m0, s8
	v_mfma_f32_16x16x32_bf16 v[52:55], v[110:113], v[130:133], v[52:55]
	global_load_lds_dwordx4 v[236:237], off
	v_mfma_f32_16x16x32_bf16 v[48:51], v[122:125], v[114:117], v[48:51]
	v_mfma_f32_16x16x32_bf16 v[44:47], v[122:125], v[118:121], v[44:47]
	v_mfma_f32_16x16x32_bf16 v[40:43], v[122:125], v[126:129], v[40:43]
	v_mfma_f32_16x16x32_bf16 v[36:39], v[122:125], v[130:133], v[36:39]
	ds_read_b128 v[110:113], v109 offset:4096
	ds_read_b128 v[122:125], v109 offset:6144
	v_lshl_add_u32 v109, v108, 1, s7
	v_add3_u32 v134, v109, v105, v106
	v_add3_u32 v109, v109, v107, v106
	s_waitcnt lgkmcnt(1)
	s_mov_b32 m0, s9
	v_mfma_f32_16x16x32_bf16 v[32:35], v[110:113], v[114:117], v[32:35]
	global_load_lds_dwordx4 v[238:239], off
	s_add_i32 s7, s5, 1
	s_cmp_lg_u32 s5, 2
	s_cselect_b32 s5, s7, 0
	v_mfma_f32_16x16x32_bf16 v[28:31], v[110:113], v[118:121], v[28:31]
	s_add_i32 s6, s6, 1
	v_mfma_f32_16x16x32_bf16 v[24:27], v[110:113], v[126:129], v[24:27]
	v_mfma_f32_16x16x32_bf16 v[20:23], v[110:113], v[130:133], v[20:23]
	ds_read_b128 v[110:113], v109
	s_waitcnt lgkmcnt(1)
	v_mfma_f32_16x16x32_bf16 v[16:19], v[122:125], v[114:117], v[16:19]
	s_mov_b32 m0, s11
	v_mfma_f32_16x16x32_bf16 v[12:15], v[122:125], v[118:121], v[12:15]
	global_load_lds_dwordx4 v[240:241], off
	v_mfma_f32_16x16x32_bf16 v[8:11], v[122:125], v[126:129], v[8:11]
	v_mfma_f32_16x16x32_bf16 v[2:5], v[122:125], v[130:133], v[2:5]
	ds_read_b128 v[114:117], v134 offset:32768
	ds_read_b128 v[118:121], v134 offset:34816
	ds_read_b128 v[122:125], v109 offset:2048
	ds_read_b128 v[126:129], v134 offset:36864
	ds_read_b128 v[130:133], v134 offset:38912
	s_waitcnt lgkmcnt(4)
	v_mfma_f32_16x16x32_bf16 v[64:67], v[110:113], v[114:117], v[64:67]
	s_waitcnt lgkmcnt(3)
	v_mfma_f32_16x16x32_bf16 v[60:63], v[110:113], v[118:121], v[60:63]
	s_waitcnt lgkmcnt(1)
	s_mov_b32 m0, s12
	v_mfma_f32_16x16x32_bf16 v[56:59], v[110:113], v[126:129], v[56:59]
	global_load_lds_dwordx4 v[242:243], off
	s_waitcnt lgkmcnt(0)
	v_mfma_f32_16x16x32_bf16 v[52:55], v[110:113], v[130:133], v[52:55]
	v_mfma_f32_16x16x32_bf16 v[48:51], v[122:125], v[114:117], v[48:51]
	v_mfma_f32_16x16x32_bf16 v[44:47], v[122:125], v[118:121], v[44:47]
	v_mfma_f32_16x16x32_bf16 v[40:43], v[122:125], v[126:129], v[40:43]
	s_mov_b32 m0, s13
	v_mfma_f32_16x16x32_bf16 v[36:39], v[122:125], v[130:133], v[36:39]
	global_load_lds_dwordx4 v[244:245], off
	ds_read_b128 v[110:113], v109 offset:4096
	ds_read_b128 v[122:125], v109 offset:6144
	s_waitcnt lgkmcnt(1)
	v_mfma_f32_16x16x32_bf16 v[32:35], v[110:113], v[114:117], v[32:35]
	v_mfma_f32_16x16x32_bf16 v[28:31], v[110:113], v[118:121], v[28:31]
	v_mfma_f32_16x16x32_bf16 v[24:27], v[110:113], v[126:129], v[24:27]
	v_mfma_f32_16x16x32_bf16 v[20:23], v[110:113], v[130:133], v[20:23]
	s_waitcnt lgkmcnt(0)
	s_mov_b32 m0, s14
	v_mfma_f32_16x16x32_bf16 v[16:19], v[122:125], v[114:117], v[16:19]
	global_load_lds_dwordx4 v[246:247], off
	s_mov_b32 m0, s15
	s_mul_i32 s8, s5, 0xc000
	s_min_u32 s7, s6, 61
	s_add_i32 s9, s8, 0xffff4000
	s_cmp_gt_i32 s5, 0
	s_cselect_b32 s9, s9, 0x18000
	s_lshl_b32 s98, s7, 7
	s_add_i32 s98, s98, 0x100
	s_add_i32 s7, s8, 0x100
	s_add_i32 s8, s9, s4
	s_add_i32 s9, s8, 0x2000
	s_add_i32 s11, s8, 0x4000
	s_add_i32 s12, s8, 0x6000
	s_add_i32 s13, s8, 0x8000
	s_add_i32 s14, s8, 0xa000
	v_mfma_f32_16x16x32_bf16 v[12:15], v[122:125], v[118:121], v[12:15]
	v_lshl_add_u64 v[236:237], v[76:77], 0, s[98:99]
	v_lshl_add_u64 v[238:239], v[80:81], 0, s[98:99]
	v_lshl_add_u64 v[240:241], v[82:83], 0, s[98:99]
	v_mfma_f32_16x16x32_bf16 v[8:11], v[122:125], v[126:129], v[8:11]
	v_lshl_add_u64 v[242:243], v[84:85], 0, s[98:99]
	v_lshl_add_u64 v[244:245], v[78:79], 0, s[98:99]
	v_lshl_add_u64 v[246:247], v[86:87], 0, s[98:99]
	v_mfma_f32_16x16x32_bf16 v[2:5], v[122:125], v[130:133], v[2:5]
	v_lshl_add_u32 v109, v104, 1, s7
	v_add3_u32 v251, v109, v105, v106
	v_add3_u32 v109, v109, v107, v106
	s_cmp_eq_u32 s6, 64
	s_cbranch_scc0 .LBB0_20
	s_setprio 0
	s_waitcnt vmcnt(0)
	v_add_u32_e32 v78, s0, v0
	v_or_b32_e32 v82, s1, v75
	s_waitcnt lgkmcnt(0)
	s_barrier
	v_ashrrev_i32_e32 v83, 31, v82
	v_ashrrev_i32_e32 v79, 31, v78
	v_lshl_add_u64 v[76:77], v[82:83], 1, s[76:77]
	v_lshlrev_b64 v[80:81], 11, v[78:79]
	s_movk_i32 s0, 0x400
	v_lshl_add_u64 v[80:81], v[76:77], 0, v[80:81]
	v_cmp_gt_i32_e32 vcc, s0, v82
	s_and_saveexec_b64 s[0:1], vcc
	s_cbranch_execz .LBB0_23
	v_bfe_u32 v79, v64, 16, 1
	v_add3_u32 v64, v64, v79, s96
	global_store_short_d16_hi v[80:81], v64, off

; __device__ __forceinline__ void lds_barrier() { asm volatile("s_waitcnt lgkmcnt(0)\n\ts_barrier" ::: "memory"); }
; template <int EPI>
; __device__ void gemm_phase(const u16* __restrict__ A, const u16* __restrict__ Bt, void* __restrict__ Cv,
;                            int N, int K, int ldc, unsigned char* ldsraw, int G) {
;     ...
;     f32x4 acc[4][4];
; #pragma unroll
;     for (int i = 0; i < 4; ++i)
; #pragma unroll
;       for (int j = 0; j < 4; ++j) acc[i][j] = (f32x4){0.f, 0.f, 0.f, 0.f};
;     const int ar0 = tid >> 3, acc4 = tid & 7;
;     const int ssw = (acc4 ^ ((ar0 >> 1) & 7)) * 8;
;     const int fx = (l15 >> 1) & 7;
;     const u16* Ag0 = A + (size_t)(m0 + ar0) * K + ssw;
;     const u16* Bg = Bt + (size_t)(n0 + ar0) * K + ssw;
;     const size_t r64 = (size_t)64 * K;
;     constexpr int STG = (GBM + GBN) * GLD;
;     const unsigned lw0 = (unsigned)__builtin_amdgcn_readfirstlane((int)(unsigned)(uintptr_t)(As + wave * 8 * GLD));
;     ...
;     GLDS(0, 0);
;     GLDS(1, 1);
;     if (__builtin_amdgcn_readfirstlane(tid) >= 256) __builtin_amdgcn_s_setprio(1);
;     int st = 0;
;     for (int kt = 0; kt < nk; ++kt) {
;       asm volatile("s_waitcnt vmcnt(6)" ::: "memory");
;       lds_barrier();
;       const int st2 = (st >= 1) ? st - 1 : 2;
;       GLDS(st2, kt + 2);
;       const u16* Asx = As + st * STG;
;       const u16* Bsx = Asx + GBM * GLD;
; #pragma unroll
;       for (int ks = 0; ks < 2; ++ks) {
;         const int fsw = ((ks * 4 + g4) ^ fx) * 8;
;         bf16x8 bfr[4];
; #pragma unroll
;         for (int jx = 0; jx < 4; ++jx) bfr[jx] = *(const bf16x8*)(Bsx + (wn * 64 + jx * 16 + l15) * GLD + fsw);
; #pragma unroll
;         for (int ix = 0; ix < 4; ++ix) {
;           const bf16x8 af = *(const bf16x8*)(Asx + (wm * 64 + ix * 16 + l15) * GLD + fsw);
; #pragma unroll
;           for (int jx = 0; jx < 4; ++jx)
;             acc[ix][jx] = __builtin_amdgcn_mfma_f32_16x16x32_bf16(af, bfr[jx], acc[ix][jx], 0, 0, 0);
;         }
;       }
;       st = (st == 2) ? 0 : st + 1;
;     }
.LBB0_156:
	v_mov_b32_e32 v2, 0
	s_mov_b32 s6, 0
	s_mov_b32 s7, 0
	v_mov_b32_e32 v3, v2
	v_mov_b32_e32 v4, v2
	v_mov_b32_e32 v5, v2
	v_mov_b32_e32 v8, v2
	v_mov_b32_e32 v9, v2
	v_mov_b32_e32 v10, v2
	v_mov_b32_e32 v11, v2
	v_mov_b32_e32 v12, v2
	v_mov_b32_e32 v13, v2
	v_mov_b32_e32 v14, v2
	v_mov_b32_e32 v15, v2
	v_mov_b32_e32 v16, v2
	v_mov_b32_e32 v17, v2
	v_mov_b32_e32 v18, v2
	v_mov_b32_e32 v19, v2
	v_mov_b32_e32 v20, v2
	v_mov_b32_e32 v21, v2
	v_mov_b32_e32 v22, v2
	v_mov_b32_e32 v23, v2
	v_mov_b32_e32 v24, v2
	v_mov_b32_e32 v25, v2
	v_mov_b32_e32 v26, v2
	v_mov_b32_e32 v27, v2
	v_mov_b32_e32 v28, v2
	v_mov_b32_e32 v29, v2
	v_mov_b32_e32 v30, v2
	v_mov_b32_e32 v31, v2
	v_mov_b32_e32 v32, v2
	v_mov_b32_e32 v33, v2
	v_mov_b32_e32 v34, v2
	v_mov_b32_e32 v35, v2
	v_mov_b32_e32 v36, v2
	v_mov_b32_e32 v37, v2
	v_mov_b32_e32 v38, v2
	v_mov_b32_e32 v39, v2
	v_mov_b32_e32 v40, v2
	v_mov_b32_e32 v41, v2
	v_mov_b32_e32 v42, v2
	v_mov_b32_e32 v43, v2
	v_mov_b32_e32 v44, v2
	v_mov_b32_e32 v45, v2
	v_mov_b32_e32 v46, v2
	v_mov_b32_e32 v47, v2
	v_mov_b32_e32 v48, v2
	v_mov_b32_e32 v49, v2
	v_mov_b32_e32 v50, v2
	v_mov_b32_e32 v51, v2
	v_mov_b32_e32 v52, v2
	v_mov_b32_e32 v53, v2
	v_mov_b32_e32 v54, v2
	v_mov_b32_e32 v55, v2
	v_mov_b32_e32 v56, v2
	v_mov_b32_e32 v57, v2
	v_mov_b32_e32 v58, v2
	s_waitcnt vmcnt(0)
	v_mov_b32_e32 v59, v2
	v_mov_b32_e32 v60, v2
	v_mov_b32_e32 v61, v2
	v_mov_b32_e32 v62, v2
	v_mov_b32_e32 v63, v2
	v_mov_b32_e32 v64, v2
	v_mov_b32_e32 v65, v2
	v_mov_b32_e32 v66, v2
	v_mov_b32_e32 v67, v2
	s_mul_i32 s9, s6, 0xc000
	s_min_u32 s8, s7, 13
	s_add_i32 s10, s9, 0xffff4000
	s_cmp_gt_i32 s6, 0
	s_cselect_b32 s10, s10, 0x18000
	s_lshl_b32 s98, s8, 7
	s_add_i32 s98, s98, 0x100
	s_add_i32 s8, s9, 0x100
	s_add_i32 s9, s10, s5
	s_add_i32 s10, s9, 0x2000
	s_add_i32 s11, s9, 0x4000
	s_add_i32 s12, s9, 0x6000
	s_add_i32 s13, s9, 0x8000
	s_add_i32 s14, s9, 0xa000
	v_lshl_add_u64 v[236:237], v[76:77], 0, s[98:99]
	v_lshl_add_u64 v[238:239], v[80:81], 0, s[98:99]
	v_lshl_add_u64 v[240:241], v[82:83], 0, s[98:99]
	v_lshl_add_u64 v[242:243], v[84:85], 0, s[98:99]
	v_lshl_add_u64 v[244:245], v[78:79], 0, s[98:99]
	v_lshl_add_u64 v[246:247], v[86:87], 0, s[98:99]
	v_lshl_add_u32 v109, v104, 1, s8
	v_add3_u32 v251, v109, v105, v106
	v_add3_u32 v109, v109, v107, v106
.LBB0_157:
	s_waitcnt vmcnt(6)
	s_waitcnt lgkmcnt(0)
	s_barrier
	s_mov_b32 s15, m0
	ds_read_b128 v[110:113], v109
	ds_read_b128 v[114:117], v251 offset:32768
	ds_read_b128 v[118:121], v251 offset:34816
	ds_read_b128 v[122:125], v109 offset:2048
	ds_read_b128 v[126:129], v251 offset:36864
	ds_read_b128 v[130:133], v251 offset:38912
	s_waitcnt lgkmcnt(4)
	v_mfma_f32_16x16x32_bf16 v[64:67], v[110:113], v[114:117], v[64:67]
	s_waitcnt lgkmcnt(3)
	v_mfma_f32_16x16x32_bf16 v[60:63], v[110:113], v[118:121], v[60:63]
	s_waitcnt lgkmcnt(1)
	v_mfma_f32_16x16x32_bf16 v[56:59], v[110:113], v[126:129], v[56:59]
	s_waitcnt lgkmcnt(0)
	s_mov_b32 m0, s9
	v_mfma_f32_16x16x32_bf16 v[52:55], v[110:113], v[130:133], v[52:55]
	global_load_lds_dwordx4 v[236:237], off
	v_mfma_f32_16x16x32_bf16 v[48:51], v[122:125], v[114:117], v[48:51]
	v_mfma_f32_16x16x32_bf16 v[44:47], v[122:125], v[118:121], v[44:47]
	v_mfma_f32_16x16x32_bf16 v[40:43], v[122:125], v[126:129], v[40:43]
	v_mfma_f32_16x16x32_bf16 v[36:39], v[122:125], v[130:133], v[36:39]
	ds_read_b128 v[110:113], v109 offset:4096
	ds_read_b128 v[122:125], v109 offset:6144
	v_lshl_add_u32 v109, v108, 1, s8
	v_add3_u32 v134, v109, v105, v106
	v_add3_u32 v109, v109, v107, v106
	s_waitcnt lgkmcnt(1)
	s_mov_b32 m0, s10
	v_mfma_f32_16x16x32_bf16 v[32:35], v[110:113], v[114:117], v[32:35]
	global_load_lds_dwordx4 v[238:239], off
	s_add_i32 s8, s6, 1
	s_cmp_lg_u32 s6, 2
	s_cselect_b32 s6, s8, 0
	v_mfma_f32_16x16x32_bf16 v[28:31], v[110:113], v[118:121], v[28:31]
	s_add_i32 s7, s7, 1
	v_mfma_f32_16x16x32_bf16 v[24:27], v[110:113], v[126:129], v[24:27]
	v_mfma_f32_16x16x32_bf16 v[20:23], v[110:113], v[130:133], v[20:23]
	ds_read_b128 v[110:113], v109
	s_waitcnt lgkmcnt(1)
	v_mfma_f32_16x16x32_bf16 v[16:19], v[122:125], v[114:117], v[16:19]
	s_mov_b32 m0, s11
	v_mfma_f32_16x16x32_bf16 v[12:15], v[122:125], v[118:121], v[12:15]
	global_load_lds_dwordx4 v[240:241], off
	v_mfma_f32_16x16x32_bf16 v[8:11], v[122:125], v[126:129], v[8:11]
	v_mfma_f32_16x16x32_bf16 v[2:5], v[122:125], v[130:133], v[2:5]
	ds_read_b128 v[114:117], v134 offset:32768
	ds_read_b128 v[118:121], v134 offset:34816
	ds_read_b128 v[122:125], v109 offset:2048
	ds_read_b128 v[126:129], v134 offset:36864
	ds_read_b128 v[130:133], v134 offset:38912
	s_waitcnt lgkmcnt(4)
	v_mfma_f32_16x16x32_bf16 v[64:67], v[110:113], v[114:117], v[64:67]
	s_waitcnt lgkmcnt(3)
	v_mfma_f32_16x16x32_bf16 v[60:63], v[110:113], v[118:121], v[60:63]
	s_waitcnt lgkmcnt(1)
	s_mov_b32 m0, s12
	v_mfma_f32_16x16x32_bf16 v[56:59], v[110:113], v[126:129], v[56:59]
	global_load_lds_dwordx4 v[242:243], off
	s_waitcnt lgkmcnt(0)
	v_mfma_f32_16x16x32_bf16 v[52:55], v[110:113], v[130:133], v[52:55]
	v_mfma_f32_16x16x32_bf16 v[48:51], v[122:125], v[114:117], v[48:51]
	v_mfma_f32_16x16x32_bf16 v[44:47], v[122:125], v[118:121], v[44:47]
	v_mfma_f32_16x16x32_bf16 v[40:43], v[122:125], v[126:129], v[40:43]
	s_mov_b32 m0, s13
	v_mfma_f32_16x16x32_bf16 v[36:39], v[122:125], v[130:133], v[36:39]
	global_load_lds_dwordx4 v[244:245], off
	ds_read_b128 v[110:113], v109 offset:4096
	ds_read_b128 v[122:125], v109 offset:6144
	s_waitcnt lgkmcnt(1)
	v_mfma_f32_16x16x32_bf16 v[32:35], v[110:113], v[114:117], v[32:35]
	v_mfma_f32_16x16x32_bf16 v[28:31], v[110:113], v[118:121], v[28:31]
	v_mfma_f32_16x16x32_bf16 v[24:27], v[110:113], v[126:129], v[24:27]
	v_mfma_f32_16x16x32_bf16 v[20:23], v[110:113], v[130:133], v[20:23]
	s_waitcnt lgkmcnt(0)
	s_mov_b32 m0, s14
	v_mfma_f32_16x16x32_bf16 v[16:19], v[122:125], v[114:117], v[16:19]
	global_load_lds_dwordx4 v[246:247], off
	s_mov_b32 m0, s15
	s_mul_i32 s9, s6, 0xc000
	s_min_u32 s8, s7, 13
	s_add_i32 s10, s9, 0xffff4000
	s_cmp_gt_i32 s6, 0
	s_cselect_b32 s10, s10, 0x18000
	s_lshl_b32 s98, s8, 7
	s_add_i32 s98, s98, 0x100
	s_add_i32 s8, s9, 0x100
	s_add_i32 s9, s10, s5
	s_add_i32 s10, s9, 0x2000
	s_add_i32 s11, s9, 0x4000
	s_add_i32 s12, s9, 0x6000
	s_add_i32 s13, s9, 0x8000
	s_add_i32 s14, s9, 0xa000
	v_mfma_f32_16x16x32_bf16 v[12:15], v[122:125], v[118:121], v[12:15]
	v_lshl_add_u64 v[236:237], v[76:77], 0, s[98:99]
	v_lshl_add_u64 v[238:239], v[80:81], 0, s[98:99]
	v_lshl_add_u64 v[240:241], v[82:83], 0, s[98:99]
	v_mfma_f32_16x16x32_bf16 v[8:11], v[122:125], v[126:129], v[8:11]
	v_lshl_add_u64 v[242:243], v[84:85], 0, s[98:99]
	v_lshl_add_u64 v[244:245], v[78:79], 0, s[98:99]
	v_lshl_add_u64 v[246:247], v[86:87], 0, s[98:99]
	v_mfma_f32_16x16x32_bf16 v[2:5], v[122:125], v[130:133], v[2:5]
	v_lshl_add_u32 v109, v104, 1, s8
	v_add3_u32 v251, v109, v105, v106
	v_add3_u32 v109, v109, v107, v106
	s_cmp_eq_u32 s7, 16
	s_cbranch_scc0 .LBB0_157
; __device__ __forceinline__ void lds_barrier() { asm volatile("s_waitcnt lgkmcnt(0)\n\ts_barrier" ::: "memory"); }
; __device__ __forceinline__ u16 f2bf(float f) {
;   u32 u = __float_as_uint(f);
;   u += 0x7fffu + ((u >> 16) & 1u);
;   return (u16)(u >> 16);
; }
; template <int EPI>
; __device__ void gemm_phase(const u16* __restrict__ A, const u16* __restrict__ Bt, void* __restrict__ Cv,
;                            int N, int K, int ldc, unsigned char* ldsraw, int G) {
;     ...
;     __builtin_amdgcn_s_setprio(0);
;     asm volatile("s_waitcnt vmcnt(0)" ::: "memory");
;     lds_barrier();
;     ...
; #pragma unroll
;     for (int i = 0; i < 4; ++i) {
; #pragma unroll
;       for (int r = 0; r < 4; ++r) {
;         const int m = m0 + wm * 64 + i * 16 + g4 * 4 + r;
;         const int nb = n0 + wn * 64 + l15;
;         if (EPI == EPI_F32) {
;           float* cp = (float*)Cv + (size_t)m * ldc + nb;
; #pragma unroll
;           for (int j = 0; j < 4; ++j) if (nb + j * 16 < N) cp[j * 16] = acc[i][j][r];
;         } else {
;           u16* cp = (u16*)Cv + (size_t)m * ldc + nb;
; #pragma unroll
;           for (int j = 0; j < 4; ++j) {
;             float v = acc[i][j][r];
;             if (EPI == EPI_RELU2) { v = fmaxf(v, 0.f); v = v * v; }
;             if (nb + j * 16 < N) cp[j * 16] = f2bf(v);
;           }
;         }
	s_setprio 0
	v_max_f32_e32 v64, v64, v64
	v_add_u32_e32 v78, s1, v0
	v_or_b32_e32 v76, s4, v75
	v_max_f32_e32 v64, 0, v64
	v_ashrrev_i32_e32 v77, 31, v76
	v_ashrrev_i32_e32 v79, 31, v78
	v_mul_f32_e32 v64, v64, v64
	v_max_f32_e32 v60, v60, v60
	v_lshl_add_u64 v[76:77], v[76:77], 1, s[18:19]
	v_lshlrev_b64 v[80:81], 13, v[78:79]
	v_bfe_u32 v79, v64, 16, 1
	v_max_f32_e32 v60, 0, v60
	s_waitcnt vmcnt(0)
	v_lshl_add_u64 v[80:81], v[76:77], 0, v[80:81]
	v_add3_u32 v64, v64, v79, s96
	v_mul_f32_e32 v60, v60, v60
	v_max_f32_e32 v56, v56, v56
	s_waitcnt lgkmcnt(0)
	s_barrier
	global_store_short_d16_hi v[80:81], v64, off
	v_bfe_u32 v64, v60, 16, 1
	v_max_f32_e32 v56, 0, v56
	v_add3_u32 v60, v60, v64, s96
	v_mul_f32_e32 v56, v56, v56
	v_max_f32_e32 v52, v52, v52
	global_store_short_d16_hi v[80:81], v60, off offset:32
	v_bfe_u32 v60, v56, 16, 1
	v_max_f32_e32 v52, 0, v52
	v_add3_u32 v56, v56, v60, s96
	v_mul_f32_e32 v52, v52, v52
	global_store_short_d16_hi v[80:81], v56, off offset:64
	v_bfe_u32 v56, v52, 16, 1
	v_add3_u32 v52, v52, v56, s96
	global_store_short_d16_hi v[80:81], v52, off offset:96
	v_max_f32_e32 v52, v65, v65
	v_or_b32_e32 v80, 1, v78
	v_max_f32_e32 v52, 0, v52
	v_ashrrev_i32_e32 v81, 31, v80
	v_mul_f32_e32 v52, v52, v52
	v_lshlrev_b64 v[80:81], 13, v[80:81]
	v_bfe_u32 v56, v52, 16, 1
	v_lshl_add_u64 v[80:81], v[76:77], 0, v[80:81]
	v_add3_u32 v52, v52, v56, s96
	global_store_short_d16_hi v[80:81], v52, off
	v_max_f32_e32 v52, v61, v61
	v_max_f32_e32 v52, 0, v52
	v_mul_f32_e32 v52, v52, v52
	v_bfe_u32 v56, v52, 16, 1
	v_add3_u32 v52, v52, v56, s96
	global_store_short_d16_hi v[80:81], v52, off offset:32
	v_max_f32_e32 v52, v57, v57
	v_max_f32_e32 v52, 0, v52
	v_mul_f32_e32 v52, v52, v52
	v_bfe_u32 v56, v52, 16, 1
	v_add3_u32 v52, v52, v56, s96
	global_store_short_d16_hi v[80:81], v52, off offset:64
	v_max_f32_e32 v52, v53, v53
	v_max_f32_e32 v52, 0, v52
	v_mul_f32_e32 v52, v52, v52
	v_bfe_u32 v53, v52, 16, 1
	v_add3_u32 v52, v52, v53, s96
	v_max_f32_e32 v56, v66, v66
	global_store_short_d16_hi v[80:81], v52, off offset:96
	v_or_b32_e32 v52, 2, v78
	v_max_f32_e32 v56, 0, v56
	v_ashrrev_i32_e32 v53, 31, v52
	v_mul_f32_e32 v56, v56, v56
	v_lshlrev_b64 v[52:53], 13, v[52:53]
	v_bfe_u32 v57, v56, 16, 1
	v_lshl_add_u64 v[52:53], v[76:77], 0, v[52:53]
	v_add3_u32 v56, v56, v57, s96
	global_store_short_d16_hi v[52:53], v56, off
	v_max_f32_e32 v56, v62, v62
	v_max_f32_e32 v56, 0, v56
	v_mul_f32_e32 v56, v56, v56
	v_bfe_u32 v57, v56, 16, 1
	v_add3_u32 v56, v56, v57, s96
	global_store_short_d16_hi v[52:53], v56, off offset:32
	v_max_f32_e32 v56, v58, v58
	v_max_f32_e32 v56, 0, v56
	v_mul_f32_e32 v56, v56, v56
	v_max_f32_e32 v54, v54, v54
	v_bfe_u32 v57, v56, 16, 1
	v_max_f32_e32 v54, 0, v54
	v_add3_u32 v56, v56, v57, s96
	v_mul_f32_e32 v54, v54, v54
	global_store_short_d16_hi v[52:53], v56, off offset:64
	v_bfe_u32 v56, v54, 16, 1
	v_add3_u32 v54, v54, v56, s96
	global_store_short_d16_hi v[52:53], v54, off offset:96
	v_max_f32_e32 v54, v67, v67
	v_or_b32_e32 v52, 3, v78
	v_max_f32_e32 v54, 0, v54
	v_ashrrev_i32_e32 v53, 31, v52
	v_mul_f32_e32 v54, v54, v54
	v_lshlrev_b64 v[52:53], 13, v[52:53]
	v_bfe_u32 v56, v54, 16, 1
	v_lshl_add_u64 v[52:53], v[76:77], 0, v[52:53]
	v_add3_u32 v54, v54, v56, s96
	global_store_short_d16_hi v[52:53], v54, off
	v_max_f32_e32 v54, v63, v63
	v_max_f32_e32 v54, 0, v54
	v_mul_f32_e32 v54, v54, v54
	v_bfe_u32 v56, v54, 16, 1
	v_add3_u32 v54, v54, v56, s96
	global_store_short_d16_hi v[52:53], v54, off offset:32
	v_max_f32_e32 v54, v59, v59
	v_max_f32_e32 v54, 0, v54
	v_mul_f32_e32 v54, v54, v54
	v_bfe_u32 v56, v54, 16, 1
	v_add3_u32 v54, v54, v56, s96
	global_store_short_d16_hi v[52:53], v54, off offset:64
	v_max_f32_e32 v54, v55, v55
	v_max_f32_e32 v54, 0, v54
	v_mul_f32_e32 v54, v54, v54
	v_bfe_u32 v55, v54, 16, 1
	v_add3_u32 v54, v54, v55, s96
	global_store_short_d16_hi v[52:53], v54, off offset:96
	v_max_f32_e32 v48, v48, v48
	v_or_b32_e32 v52, 16, v78
	v_max_f32_e32 v48, 0, v48
	v_ashrrev_i32_e32 v53, 31, v52
	v_mul_f32_e32 v48, v48, v48
	v_max_f32_e32 v44, v44, v44
	v_lshlrev_b64 v[52:53], 13, v[52:53]
	v_bfe_u32 v54, v48, 16, 1
	v_max_f32_e32 v44, 0, v44
	v_lshl_add_u64 v[52:53], v[76:77], 0, v[52:53]
	v_add3_u32 v48, v48, v54, s96
	v_mul_f32_e32 v44, v44, v44
	v_max_f32_e32 v40, v40, v40
	global_store_short_d16_hi v[52:53], v48, off
	v_bfe_u32 v48, v44, 16, 1
	v_max_f32_e32 v40, 0, v40
	v_add3_u32 v44, v44, v48, s96
	v_mul_f32_e32 v40, v40, v40
	v_max_f32_e32 v36, v36, v36
	global_store_short_d16_hi v[52:53], v44, off offset:32
	v_bfe_u32 v44, v40, 16, 1
	v_max_f32_e32 v36, 0, v36
	v_add3_u32 v40, v40, v44, s96
	v_mul_f32_e32 v36, v36, v36
	global_store_short_d16_hi v[52:53], v40, off offset:64
	v_bfe_u32 v40, v36, 16, 1
	v_add3_u32 v36, v36, v40, s96
	global_store_short_d16_hi v[52:53], v36, off offset:96
	v_max_f32_e32 v36, v49, v49
	v_or_b32_e32 v52, 17, v78
	v_max_f32_e32 v36, 0, v36
	v_ashrrev_i32_e32 v53, 31, v52
	v_mul_f32_e32 v36, v36, v36
	v_lshlrev_b64 v[52:53], 13, v[52:53]
	v_bfe_u32 v40, v36, 16, 1
	v_lshl_add_u64 v[52:53], v[76:77], 0, v[52:53]
	v_add3_u32 v36, v36, v40, s96
	global_store_short_d16_hi v[52:53], v36, off
	v_max_f32_e32 v36, v45, v45
	v_max_f32_e32 v36, 0, v36
	v_mul_f32_e32 v36, v36, v36
	v_bfe_u32 v40, v36, 16, 1
	v_add3_u32 v36, v36, v40, s96
	global_store_short_d16_hi v[52:53], v36, off offset:32
	v_max_f32_e32 v36, v41, v41
	v_max_f32_e32 v36, 0, v36
	v_mul_f32_e32 v36, v36, v36
	v_bfe_u32 v40, v36, 16, 1
	v_add3_u32 v36, v36, v40, s96
	global_store_short_d16_hi v[52:53], v36, off offset:64
	v_max_f32_e32 v36, v37, v37
	v_max_f32_e32 v36, 0, v36
	v_mul_f32_e32 v36, v36, v36
; template <int EPI>
; __device__ void gemm_phase(const u16* __restrict__ A, const u16* __restrict__ Bt, void* __restrict__ Cv,
;                            int N, int K, int ldc, unsigned char* ldsraw, int G) {
;     ...
;     for (int i = 0; i < 4; ++i) {
; #pragma unroll
;       for (int r = 0; r < 4; ++r) {
;         const int m = m0 + wm * 64 + i * 16 + g4 * 4 + r;
;         const int nb = n0 + wn * 64 + l15;
;         if (EPI == EPI_F32) {
;           float* cp = (float*)Cv + (size_t)m * ldc + nb;
; #pragma unroll
;           for (int j = 0; j < 4; ++j) if (nb + j * 16 < N) cp[j * 16] = acc[i][j][r];
;         } else {
;           u16* cp = (u16*)Cv + (size_t)m * ldc + nb;
; #pragma unroll
;           for (int j = 0; j < 4; ++j) {
;             float v = acc[i][j][r];
;             if (EPI == EPI_RELU2) { v = fmaxf(v, 0.f); v = v * v; }
;             if (nb + j * 16 < N) cp[j * 16] = f2bf(v);
;           }
;         }
	v_bfe_u32 v37, v36, 16, 1
	v_add3_u32 v36, v36, v37, s96
	v_max_f32_e32 v40, v50, v50
	global_store_short_d16_hi v[52:53], v36, off offset:96
	v_or_b32_e32 v36, 18, v78
	v_max_f32_e32 v40, 0, v40
	v_ashrrev_i32_e32 v37, 31, v36
	v_mul_f32_e32 v40, v40, v40
	v_lshlrev_b64 v[36:37], 13, v[36:37]
	v_bfe_u32 v41, v40, 16, 1
	v_lshl_add_u64 v[36:37], v[76:77], 0, v[36:37]
	v_add3_u32 v40, v40, v41, s96
	global_store_short_d16_hi v[36:37], v40, off
	v_max_f32_e32 v40, v46, v46
	v_max_f32_e32 v40, 0, v40
	v_mul_f32_e32 v40, v40, v40
	v_bfe_u32 v41, v40, 16, 1
	v_add3_u32 v40, v40, v41, s96
	global_store_short_d16_hi v[36:37], v40, off offset:32
	v_max_f32_e32 v40, v42, v42
	v_max_f32_e32 v40, 0, v40
	v_mul_f32_e32 v40, v40, v40
	v_max_f32_e32 v38, v38, v38
	v_bfe_u32 v41, v40, 16, 1
	v_max_f32_e32 v38, 0, v38
	v_add3_u32 v40, v40, v41, s96
	v_mul_f32_e32 v38, v38, v38
	global_store_short_d16_hi v[36:37], v40, off offset:64
	v_bfe_u32 v40, v38, 16, 1
	v_add3_u32 v38, v38, v40, s96
	global_store_short_d16_hi v[36:37], v38, off offset:96
	v_max_f32_e32 v38, v51, v51
	v_or_b32_e32 v36, 19, v78
	v_max_f32_e32 v38, 0, v38
	v_ashrrev_i32_e32 v37, 31, v36
	v_mul_f32_e32 v38, v38, v38
	v_lshlrev_b64 v[36:37], 13, v[36:37]
	v_bfe_u32 v40, v38, 16, 1
	v_lshl_add_u64 v[36:37], v[76:77], 0, v[36:37]
	v_add3_u32 v38, v38, v40, s96
	global_store_short_d16_hi v[36:37], v38, off
	v_max_f32_e32 v38, v47, v47
	v_max_f32_e32 v38, 0, v38
	v_mul_f32_e32 v38, v38, v38
	v_bfe_u32 v40, v38, 16, 1
	v_add3_u32 v38, v38, v40, s96
	global_store_short_d16_hi v[36:37], v38, off offset:32
	v_max_f32_e32 v38, v43, v43
	v_max_f32_e32 v38, 0, v38
	v_mul_f32_e32 v38, v38, v38
	v_bfe_u32 v40, v38, 16, 1
	v_add3_u32 v38, v38, v40, s96
	global_store_short_d16_hi v[36:37], v38, off offset:64
	v_max_f32_e32 v38, v39, v39
	v_max_f32_e32 v38, 0, v38
	v_mul_f32_e32 v38, v38, v38
	v_bfe_u32 v39, v38, 16, 1
	v_add3_u32 v38, v38, v39, s96
	global_store_short_d16_hi v[36:37], v38, off offset:96
	v_max_f32_e32 v32, v32, v32
	v_or_b32_e32 v36, 32, v78
	v_max_f32_e32 v32, 0, v32
	v_ashrrev_i32_e32 v37, 31, v36
	v_mul_f32_e32 v32, v32, v32
	v_max_f32_e32 v28, v28, v28
	v_lshlrev_b64 v[36:37], 13, v[36:37]
	v_bfe_u32 v38, v32, 16, 1
	v_max_f32_e32 v28, 0, v28
	v_lshl_add_u64 v[36:37], v[76:77], 0, v[36:37]
	v_add3_u32 v32, v32, v38, s96
	v_mul_f32_e32 v28, v28, v28
	v_max_f32_e32 v24, v24, v24
	global_store_short_d16_hi v[36:37], v32, off
	v_bfe_u32 v32, v28, 16, 1
	v_max_f32_e32 v24, 0, v24
	v_add3_u32 v28, v28, v32, s96
	v_mul_f32_e32 v24, v24, v24
	v_max_f32_e32 v20, v20, v20
	global_store_short_d16_hi v[36:37], v28, off offset:32
	v_bfe_u32 v28, v24, 16, 1
	v_max_f32_e32 v20, 0, v20
	v_add3_u32 v24, v24, v28, s96
	v_mul_f32_e32 v20, v20, v20
	global_store_short_d16_hi v[36:37], v24, off offset:64
	v_bfe_u32 v24, v20, 16, 1
	v_add3_u32 v20, v20, v24, s96
	global_store_short_d16_hi v[36:37], v20, off offset:96
	v_max_f32_e32 v20, v33, v33
	v_or_b32_e32 v36, 33, v78
	v_max_f32_e32 v20, 0, v20
	v_ashrrev_i32_e32 v37, 31, v36
	v_mul_f32_e32 v20, v20, v20
	v_lshlrev_b64 v[36:37], 13, v[36:37]
	v_bfe_u32 v24, v20, 16, 1
	v_lshl_add_u64 v[36:37], v[76:77], 0, v[36:37]
	v_add3_u32 v20, v20, v24, s96
	global_store_short_d16_hi v[36:37], v20, off
	v_max_f32_e32 v20, v29, v29
	v_max_f32_e32 v20, 0, v20
	v_mul_f32_e32 v20, v20, v20
	v_bfe_u32 v24, v20, 16, 1
	v_add3_u32 v20, v20, v24, s96
	global_store_short_d16_hi v[36:37], v20, off offset:32
	v_max_f32_e32 v20, v25, v25
	v_max_f32_e32 v20, 0, v20
	v_mul_f32_e32 v20, v20, v20
	v_bfe_u32 v24, v20, 16, 1
	v_add3_u32 v20, v20, v24, s96
	global_store_short_d16_hi v[36:37], v20, off offset:64
	v_max_f32_e32 v20, v21, v21
	v_max_f32_e32 v20, 0, v20
	v_mul_f32_e32 v20, v20, v20
	v_bfe_u32 v21, v20, 16, 1
	v_add3_u32 v20, v20, v21, s96
	v_max_f32_e32 v24, v34, v34
	global_store_short_d16_hi v[36:37], v20, off offset:96
	v_or_b32_e32 v20, 34, v78
	v_max_f32_e32 v24, 0, v24
	v_ashrrev_i32_e32 v21, 31, v20
	v_mul_f32_e32 v24, v24, v24
	v_lshlrev_b64 v[20:21], 13, v[20:21]
	v_bfe_u32 v25, v24, 16, 1
	v_lshl_add_u64 v[20:21], v[76:77], 0, v[20:21]
	v_add3_u32 v24, v24, v25, s96
	global_store_short_d16_hi v[20:21], v24, off
	v_max_f32_e32 v24, v30, v30
	v_max_f32_e32 v24, 0, v24
	v_mul_f32_e32 v24, v24, v24
	v_bfe_u32 v25, v24, 16, 1
	v_add3_u32 v24, v24, v25, s96
	global_store_short_d16_hi v[20:21], v24, off offset:32
	v_max_f32_e32 v24, v26, v26
	v_max_f32_e32 v24, 0, v24
	v_mul_f32_e32 v24, v24, v24
	v_max_f32_e32 v22, v22, v22
	v_bfe_u32 v25, v24, 16, 1
	v_max_f32_e32 v22, 0, v22
	v_add3_u32 v24, v24, v25, s96
	v_mul_f32_e32 v22, v22, v22
	global_store_short_d16_hi v[20:21], v24, off offset:64
; template <int EPI>
; __device__ void gemm_phase(const u16* __restrict__ A, const u16* __restrict__ Bt, void* __restrict__ Cv,
;                            int N, int K, int ldc, unsigned char* ldsraw, int G) {
;     ...
;   for (int tile = t_begin; tile < t_end; tile += t_step) {
;     ...
;     for (int i = 0; i < 4; ++i) {
; #pragma unroll
;       for (int r = 0; r < 4; ++r) {
;         const int m = m0 + wm * 64 + i * 16 + g4 * 4 + r;
;         const int nb = n0 + wn * 64 + l15;
;         if (EPI == EPI_F32) {
;           float* cp = (float*)Cv + (size_t)m * ldc + nb;
; #pragma unroll
;           for (int j = 0; j < 4; ++j) if (nb + j * 16 < N) cp[j * 16] = acc[i][j][r];
;         } else {
;           u16* cp = (u16*)Cv + (size_t)m * ldc + nb;
; #pragma unroll
;           for (int j = 0; j < 4; ++j) {
;             float v = acc[i][j][r];
;             if (EPI == EPI_RELU2) { v = fmaxf(v, 0.f); v = v * v; }
;             if (nb + j * 16 < N) cp[j * 16] = f2bf(v);
;           }
;         }
;       }
;       __builtin_amdgcn_sched_barrier(0);
;     }
;   }
	v_bfe_u32 v24, v22, 16, 1
	v_add3_u32 v22, v22, v24, s96
	global_store_short_d16_hi v[20:21], v22, off offset:96
	v_max_f32_e32 v22, v35, v35
	v_or_b32_e32 v20, 35, v78
	v_max_f32_e32 v22, 0, v22
	v_ashrrev_i32_e32 v21, 31, v20
	v_mul_f32_e32 v22, v22, v22
	v_lshlrev_b64 v[20:21], 13, v[20:21]
	v_bfe_u32 v24, v22, 16, 1
	v_lshl_add_u64 v[20:21], v[76:77], 0, v[20:21]
	v_add3_u32 v22, v22, v24, s96
	global_store_short_d16_hi v[20:21], v22, off
	v_max_f32_e32 v22, v31, v31
	v_max_f32_e32 v22, 0, v22
	v_mul_f32_e32 v22, v22, v22
	v_bfe_u32 v24, v22, 16, 1
	v_add3_u32 v22, v22, v24, s96
	global_store_short_d16_hi v[20:21], v22, off offset:32
	v_max_f32_e32 v22, v27, v27
	v_max_f32_e32 v22, 0, v22
	v_mul_f32_e32 v22, v22, v22
	v_bfe_u32 v24, v22, 16, 1
	v_add3_u32 v22, v22, v24, s96
	global_store_short_d16_hi v[20:21], v22, off offset:64
	v_max_f32_e32 v22, v23, v23
	v_max_f32_e32 v22, 0, v22
	v_mul_f32_e32 v22, v22, v22
	v_bfe_u32 v23, v22, 16, 1
	v_add3_u32 v22, v22, v23, s96
	global_store_short_d16_hi v[20:21], v22, off offset:96
	v_max_f32_e32 v16, v16, v16
	v_or_b32_e32 v20, 48, v78
	v_max_f32_e32 v16, 0, v16
	v_ashrrev_i32_e32 v21, 31, v20
	v_mul_f32_e32 v16, v16, v16
	v_max_f32_e32 v12, v12, v12
	v_lshlrev_b64 v[20:21], 13, v[20:21]
	v_bfe_u32 v22, v16, 16, 1
	v_max_f32_e32 v12, 0, v12
	v_lshl_add_u64 v[20:21], v[76:77], 0, v[20:21]
	v_add3_u32 v16, v16, v22, s96
	v_mul_f32_e32 v12, v12, v12
	v_max_f32_e32 v8, v8, v8
	global_store_short_d16_hi v[20:21], v16, off
	v_bfe_u32 v16, v12, 16, 1
	v_max_f32_e32 v8, 0, v8
	v_add3_u32 v12, v12, v16, s96
	v_mul_f32_e32 v8, v8, v8
	v_max_f32_e32 v2, v2, v2
	global_store_short_d16_hi v[20:21], v12, off offset:32
	v_bfe_u32 v12, v8, 16, 1
	v_max_f32_e32 v2, 0, v2
	v_add3_u32 v8, v8, v12, s96
	v_mul_f32_e32 v2, v2, v2
	global_store_short_d16_hi v[20:21], v8, off offset:64
	v_bfe_u32 v8, v2, 16, 1
	v_add3_u32 v2, v2, v8, s96
	global_store_short_d16_hi v[20:21], v2, off offset:96
	v_max_f32_e32 v2, v17, v17
	v_or_b32_e32 v20, 49, v78
	v_max_f32_e32 v2, 0, v2
	v_ashrrev_i32_e32 v21, 31, v20
	v_mul_f32_e32 v2, v2, v2
	v_lshlrev_b64 v[20:21], 13, v[20:21]
	v_bfe_u32 v8, v2, 16, 1
	v_lshl_add_u64 v[20:21], v[76:77], 0, v[20:21]
	v_add3_u32 v2, v2, v8, s96
	global_store_short_d16_hi v[20:21], v2, off
	v_max_f32_e32 v2, v13, v13
	v_max_f32_e32 v2, 0, v2
	v_mul_f32_e32 v2, v2, v2
	v_bfe_u32 v8, v2, 16, 1
	v_add3_u32 v2, v2, v8, s96
	global_store_short_d16_hi v[20:21], v2, off offset:32
	v_max_f32_e32 v2, v9, v9
	v_max_f32_e32 v2, 0, v2
	v_mul_f32_e32 v2, v2, v2
	v_bfe_u32 v8, v2, 16, 1
	v_add3_u32 v2, v2, v8, s96
	global_store_short_d16_hi v[20:21], v2, off offset:64
	v_max_f32_e32 v2, v3, v3
	v_max_f32_e32 v2, 0, v2
	v_mul_f32_e32 v2, v2, v2
	v_bfe_u32 v3, v2, 16, 1
	v_add3_u32 v2, v2, v3, s96
	v_max_f32_e32 v8, v18, v18
	global_store_short_d16_hi v[20:21], v2, off offset:96
	v_or_b32_e32 v2, 50, v78
	v_max_f32_e32 v8, 0, v8
	v_ashrrev_i32_e32 v3, 31, v2
	v_mul_f32_e32 v8, v8, v8
	v_lshlrev_b64 v[2:3], 13, v[2:3]
	v_bfe_u32 v9, v8, 16, 1
	v_lshl_add_u64 v[2:3], v[76:77], 0, v[2:3]
	v_add3_u32 v8, v8, v9, s96
	global_store_short_d16_hi v[2:3], v8, off
	v_max_f32_e32 v8, v14, v14
	v_max_f32_e32 v8, 0, v8
	v_mul_f32_e32 v8, v8, v8
	v_bfe_u32 v9, v8, 16, 1
	v_add3_u32 v8, v8, v9, s96
	global_store_short_d16_hi v[2:3], v8, off offset:32
	v_max_f32_e32 v8, v10, v10
	v_max_f32_e32 v8, 0, v8
	v_mul_f32_e32 v8, v8, v8
	v_max_f32_e32 v4, v4, v4
	v_bfe_u32 v9, v8, 16, 1
	v_max_f32_e32 v4, 0, v4
	v_add3_u32 v8, v8, v9, s96
	v_mul_f32_e32 v4, v4, v4
	global_store_short_d16_hi v[2:3], v8, off offset:64
	v_bfe_u32 v8, v4, 16, 1
	v_add3_u32 v4, v4, v8, s96
	global_store_short_d16_hi v[2:3], v4, off offset:96
	v_max_f32_e32 v4, v19, v19
	v_or_b32_e32 v2, 51, v78
	v_max_f32_e32 v4, 0, v4
	v_ashrrev_i32_e32 v3, 31, v2
	v_mul_f32_e32 v4, v4, v4
	v_lshlrev_b64 v[2:3], 13, v[2:3]
	v_bfe_u32 v8, v4, 16, 1
	v_lshl_add_u64 v[2:3], v[76:77], 0, v[2:3]
	v_add3_u32 v4, v4, v8, s96
	global_store_short_d16_hi v[2:3], v4, off
	v_max_f32_e32 v4, v15, v15
	v_max_f32_e32 v4, 0, v4
	v_mul_f32_e32 v4, v4, v4
	v_bfe_u32 v8, v4, 16, 1
	v_add3_u32 v4, v4, v8, s96
	global_store_short_d16_hi v[2:3], v4, off offset:32
	v_max_f32_e32 v4, v11, v11
	v_max_f32_e32 v4, 0, v4
	v_mul_f32_e32 v4, v4, v4
	v_bfe_u32 v8, v4, 16, 1
	v_add3_u32 v4, v4, v8, s96
	global_store_short_d16_hi v[2:3], v4, off offset:64
	v_max_f32_e32 v4, v5, v5
	v_max_f32_e32 v4, 0, v4
	v_mul_f32_e32 v4, v4, v4
	v_bfe_u32 v5, v4, 16, 1
	v_add3_u32 v4, v4, v5, s96
	global_store_short_d16_hi v[2:3], v4, off offset:96
	s_add_i32 s0, s0, s33
	s_cmpk_gt_i32 s0, 0x7ff
	s_cbranch_scc0 .LBB0_154

; template <int EPI>
; __device__ void gemm_phase(const u16* __restrict__ A, const u16* __restrict__ Bt, void* __restrict__ Cv,
;                            int N, int K, int ldc, unsigned char* ldsraw, int G) {
;     ...
;     f32x4 acc[4][4];
; #pragma unroll
;     for (int i = 0; i < 4; ++i)
; #pragma unroll
;       for (int j = 0; j < 4; ++j) acc[i][j] = (f32x4){0.f, 0.f, 0.f, 0.f};
;     const int ar0 = tid >> 3, acc4 = tid & 7;
;     const int ssw = (acc4 ^ ((ar0 >> 1) & 7)) * 8;
;     const int fx = (l15 >> 1) & 7;
;     const u16* Ag0 = A + (size_t)(m0 + ar0) * K + ssw;
;     const u16* Bg = Bt + (size_t)(n0 + ar0) * K + ssw;
;     const size_t r64 = (size_t)64 * K;
;     constexpr int STG = (GBM + GBN) * GLD;
;     const unsigned lw0 = (unsigned)__builtin_amdgcn_readfirstlane((int)(unsigned)(uintptr_t)(As + wave * 8 * GLD));
;     ...
;     GLDS(0, 0);
;     GLDS(1, 1);
.LBB0_175:
	v_mov_b32_e32 v2, 0
	s_mov_b32 s5, 0
	s_mov_b32 s6, 0
	v_mov_b32_e32 v3, v2
	v_mov_b32_e32 v4, v2
	v_mov_b32_e32 v5, v2
	v_mov_b32_e32 v8, v2
	v_mov_b32_e32 v9, v2
	v_mov_b32_e32 v10, v2
	v_mov_b32_e32 v11, v2
	v_mov_b32_e32 v12, v2
	v_mov_b32_e32 v13, v2
	v_mov_b32_e32 v14, v2
	v_mov_b32_e32 v15, v2
	v_mov_b32_e32 v16, v2
	v_mov_b32_e32 v17, v2
	v_mov_b32_e32 v18, v2
	v_mov_b32_e32 v19, v2
	v_mov_b32_e32 v20, v2
	v_mov_b32_e32 v21, v2
	v_mov_b32_e32 v22, v2
	v_mov_b32_e32 v23, v2
	v_mov_b32_e32 v24, v2
	v_mov_b32_e32 v25, v2
	v_mov_b32_e32 v26, v2
	v_mov_b32_e32 v27, v2
	v_mov_b32_e32 v28, v2
	v_mov_b32_e32 v29, v2
	v_mov_b32_e32 v30, v2
	v_mov_b32_e32 v31, v2
	v_mov_b32_e32 v32, v2
	v_mov_b32_e32 v33, v2
	v_mov_b32_e32 v34, v2
	v_mov_b32_e32 v35, v2
	v_mov_b32_e32 v36, v2
	v_mov_b32_e32 v37, v2
	v_mov_b32_e32 v38, v2
	v_mov_b32_e32 v39, v2
	v_mov_b32_e32 v40, v2
	v_mov_b32_e32 v41, v2
	v_mov_b32_e32 v42, v2
	v_mov_b32_e32 v43, v2
	v_mov_b32_e32 v44, v2
	v_mov_b32_e32 v45, v2
	v_mov_b32_e32 v46, v2
	v_mov_b32_e32 v47, v2
	v_mov_b32_e32 v48, v2
	v_mov_b32_e32 v49, v2
	v_mov_b32_e32 v50, v2
	v_mov_b32_e32 v51, v2
	v_mov_b32_e32 v52, v2
	v_mov_b32_e32 v53, v2
	v_mov_b32_e32 v54, v2
	v_mov_b32_e32 v55, v2
	v_mov_b32_e32 v56, v2
	v_mov_b32_e32 v57, v2
	v_mov_b32_e32 v58, v2
	s_waitcnt vmcnt(0)
	v_mov_b32_e32 v59, v2
	v_mov_b32_e32 v60, v2
	v_mov_b32_e32 v61, v2
	v_mov_b32_e32 v62, v2
	v_mov_b32_e32 v63, v2
	v_mov_b32_e32 v64, v2
	v_mov_b32_e32 v65, v2
	v_mov_b32_e32 v66, v2
	v_mov_b32_e32 v67, v2
	s_mul_i32 s8, s5, 0xc000
	s_min_u32 s7, s6, 13
	s_add_i32 s9, s8, 0xffff4000
	s_cmp_gt_i32 s5, 0
	s_cselect_b32 s9, s9, 0x18000
	s_lshl_b32 s98, s7, 7
	s_add_i32 s98, s98, 0x100
	s_add_i32 s7, s8, 0x100
	s_add_i32 s8, s9, s4
	s_add_i32 s9, s8, 0x2000
	s_add_i32 s11, s8, 0x4000
	s_add_i32 s12, s8, 0x6000
	s_add_i32 s13, s8, 0x8000
	s_add_i32 s14, s8, 0xa000
	v_lshl_add_u64 v[236:237], v[76:77], 0, s[98:99]
	v_lshl_add_u64 v[238:239], v[80:81], 0, s[98:99]
	v_lshl_add_u64 v[240:241], v[82:83], 0, s[98:99]
	v_lshl_add_u64 v[242:243], v[84:85], 0, s[98:99]
	v_lshl_add_u64 v[244:245], v[78:79], 0, s[98:99]
	v_lshl_add_u64 v[246:247], v[86:87], 0, s[98:99]
	v_lshl_add_u32 v109, v104, 1, s7
	v_add3_u32 v251, v109, v105, v106
	v_add3_u32 v109, v109, v107, v106
; __device__ __forceinline__ void lds_barrier() { asm volatile("s_waitcnt lgkmcnt(0)\n\ts_barrier" ::: "memory"); }
; template <int EPI>
; __device__ void gemm_phase(const u16* __restrict__ A, const u16* __restrict__ Bt, void* __restrict__ Cv,
;                            int N, int K, int ldc, unsigned char* ldsraw, int G) {
;     ...
;     for (int kt = 0; kt < nk; ++kt) {
;       asm volatile("s_waitcnt vmcnt(6)" ::: "memory");
;       lds_barrier();
;       const int st2 = (st >= 1) ? st - 1 : 2;
;       GLDS(st2, kt + 2);
;       const u16* Asx = As + st * STG;
;       const u16* Bsx = Asx + GBM * GLD;
; #pragma unroll
;       for (int ks = 0; ks < 2; ++ks) {
;         const int fsw = ((ks * 4 + g4) ^ fx) * 8;
;         bf16x8 bfr[4];
; #pragma unroll
;         for (int jx = 0; jx < 4; ++jx) bfr[jx] = *(const bf16x8*)(Bsx + (wn * 64 + jx * 16 + l15) * GLD + fsw);
; #pragma unroll
;         for (int ix = 0; ix < 4; ++ix) {
;           const bf16x8 af = *(const bf16x8*)(Asx + (wm * 64 + ix * 16 + l15) * GLD + fsw);
; #pragma unroll
;           for (int jx = 0; jx < 4; ++jx)
;             acc[ix][jx] = __builtin_amdgcn_mfma_f32_16x16x32_bf16(af, bfr[jx], acc[ix][jx], 0, 0, 0);
;         }
;       }
;       st = (st == 2) ? 0 : st + 1;
;     }
;     __builtin_amdgcn_s_setprio(0);
;     asm volatile("s_waitcnt vmcnt(0)" ::: "memory");
;     lds_barrier();
;     ...
; #pragma unroll
;     for (int i = 0; i < 4; ++i) {
; #pragma unroll
;       for (int r = 0; r < 4; ++r) {
;         const int m = m0 + wm * 64 + i * 16 + g4 * 4 + r;
;         const int nb = n0 + wn * 64 + l15;
;         if (EPI == EPI_F32) {
;           float* cp = (float*)Cv + (size_t)m * ldc + nb;
; #pragma unroll
;           for (int j = 0; j < 4; ++j) if (nb + j * 16 < N) cp[j * 16] = acc[i][j][r];
;         } else {
;           u16* cp = (u16*)Cv + (size_t)m * ldc + nb;
; #pragma unroll
;           for (int j = 0; j < 4; ++j) {
;             float v = acc[i][j][r];
;             if (EPI == EPI_RELU2) { v = fmaxf(v, 0.f); v = v * v; }
;             if (nb + j * 16 < N) cp[j * 16] = f2bf(v);
.LBB0_176:
	s_waitcnt vmcnt(6)
	s_waitcnt lgkmcnt(0)
	s_barrier
	s_mov_b32 s15, m0
	ds_read_b128 v[110:113], v109
	ds_read_b128 v[114:117], v251 offset:32768
	ds_read_b128 v[118:121], v251 offset:34816
	ds_read_b128 v[122:125], v109 offset:2048
	ds_read_b128 v[126:129], v251 offset:36864
	ds_read_b128 v[130:133], v251 offset:38912
	s_waitcnt lgkmcnt(4)
	v_mfma_f32_16x16x32_bf16 v[64:67], v[110:113], v[114:117], v[64:67]
	s_waitcnt lgkmcnt(3)
	v_mfma_f32_16x16x32_bf16 v[60:63], v[110:113], v[118:121], v[60:63]
	s_waitcnt lgkmcnt(1)
	v_mfma_f32_16x16x32_bf16 v[56:59], v[110:113], v[126:129], v[56:59]
	s_waitcnt lgkmcnt(0)
	s_mov_b32 m0, s8
	v_mfma_f32_16x16x32_bf16 v[52:55], v[110:113], v[130:133], v[52:55]
	global_load_lds_dwordx4 v[236:237], off
	v_mfma_f32_16x16x32_bf16 v[48:51], v[122:125], v[114:117], v[48:51]
	v_mfma_f32_16x16x32_bf16 v[44:47], v[122:125], v[118:121], v[44:47]
	v_mfma_f32_16x16x32_bf16 v[40:43], v[122:125], v[126:129], v[40:43]
	v_mfma_f32_16x16x32_bf16 v[36:39], v[122:125], v[130:133], v[36:39]
	ds_read_b128 v[110:113], v109 offset:4096
	ds_read_b128 v[122:125], v109 offset:6144
	v_lshl_add_u32 v109, v108, 1, s7
	v_add3_u32 v134, v109, v105, v106
	v_add3_u32 v109, v109, v107, v106
	s_waitcnt lgkmcnt(1)
	s_mov_b32 m0, s9
	v_mfma_f32_16x16x32_bf16 v[32:35], v[110:113], v[114:117], v[32:35]
	global_load_lds_dwordx4 v[238:239], off
	s_add_i32 s7, s5, 1
	s_cmp_lg_u32 s5, 2
	s_cselect_b32 s5, s7, 0
	v_mfma_f32_16x16x32_bf16 v[28:31], v[110:113], v[118:121], v[28:31]
	s_add_i32 s6, s6, 1
	v_mfma_f32_16x16x32_bf16 v[24:27], v[110:113], v[126:129], v[24:27]
	v_mfma_f32_16x16x32_bf16 v[20:23], v[110:113], v[130:133], v[20:23]
	ds_read_b128 v[110:113], v109
	s_waitcnt lgkmcnt(1)
	v_mfma_f32_16x16x32_bf16 v[16:19], v[122:125], v[114:117], v[16:19]
	s_mov_b32 m0, s11
	v_mfma_f32_16x16x32_bf16 v[12:15], v[122:125], v[118:121], v[12:15]
	global_load_lds_dwordx4 v[240:241], off
	v_mfma_f32_16x16x32_bf16 v[8:11], v[122:125], v[126:129], v[8:11]
	v_mfma_f32_16x16x32_bf16 v[2:5], v[122:125], v[130:133], v[2:5]
	ds_read_b128 v[114:117], v134 offset:32768
	ds_read_b128 v[118:121], v134 offset:34816
	ds_read_b128 v[122:125], v109 offset:2048
	ds_read_b128 v[126:129], v134 offset:36864
	ds_read_b128 v[130:133], v134 offset:38912
	s_waitcnt lgkmcnt(4)
	v_mfma_f32_16x16x32_bf16 v[64:67], v[110:113], v[114:117], v[64:67]
	s_waitcnt lgkmcnt(3)
	v_mfma_f32_16x16x32_bf16 v[60:63], v[110:113], v[118:121], v[60:63]
	s_waitcnt lgkmcnt(1)
	s_mov_b32 m0, s12
	v_mfma_f32_16x16x32_bf16 v[56:59], v[110:113], v[126:129], v[56:59]
	global_load_lds_dwordx4 v[242:243], off
	s_waitcnt lgkmcnt(0)
	v_mfma_f32_16x16x32_bf16 v[52:55], v[110:113], v[130:133], v[52:55]
	v_mfma_f32_16x16x32_bf16 v[48:51], v[122:125], v[114:117], v[48:51]
	v_mfma_f32_16x16x32_bf16 v[44:47], v[122:125], v[118:121], v[44:47]
	v_mfma_f32_16x16x32_bf16 v[40:43], v[122:125], v[126:129], v[40:43]
	s_mov_b32 m0, s13
	v_mfma_f32_16x16x32_bf16 v[36:39], v[122:125], v[130:133], v[36:39]
	global_load_lds_dwordx4 v[244:245], off
	ds_read_b128 v[110:113], v109 offset:4096
	ds_read_b128 v[122:125], v109 offset:6144
	s_waitcnt lgkmcnt(1)
	v_mfma_f32_16x16x32_bf16 v[32:35], v[110:113], v[114:117], v[32:35]
	v_mfma_f32_16x16x32_bf16 v[28:31], v[110:113], v[118:121], v[28:31]
	v_mfma_f32_16x16x32_bf16 v[24:27], v[110:113], v[126:129], v[24:27]
	v_mfma_f32_16x16x32_bf16 v[20:23], v[110:113], v[130:133], v[20:23]
	s_waitcnt lgkmcnt(0)
	s_mov_b32 m0, s14
	v_mfma_f32_16x16x32_bf16 v[16:19], v[122:125], v[114:117], v[16:19]
	global_load_lds_dwordx4 v[246:247], off
	s_mov_b32 m0, s15
	s_mul_i32 s8, s5, 0xc000
	s_min_u32 s7, s6, 13
	s_add_i32 s9, s8, 0xffff4000
	s_cmp_gt_i32 s5, 0
	s_cselect_b32 s9, s9, 0x18000
	s_lshl_b32 s98, s7, 7
	s_add_i32 s98, s98, 0x100
	s_add_i32 s7, s8, 0x100
	s_add_i32 s8, s9, s4
	s_add_i32 s9, s8, 0x2000
	s_add_i32 s11, s8, 0x4000
	s_add_i32 s12, s8, 0x6000
	s_add_i32 s13, s8, 0x8000
	s_add_i32 s14, s8, 0xa000
	v_mfma_f32_16x16x32_bf16 v[12:15], v[122:125], v[118:121], v[12:15]
	v_lshl_add_u64 v[236:237], v[76:77], 0, s[98:99]
	v_lshl_add_u64 v[238:239], v[80:81], 0, s[98:99]
	v_lshl_add_u64 v[240:241], v[82:83], 0, s[98:99]
	v_mfma_f32_16x16x32_bf16 v[8:11], v[122:125], v[126:129], v[8:11]
	v_lshl_add_u64 v[242:243], v[84:85], 0, s[98:99]
	v_lshl_add_u64 v[244:245], v[78:79], 0, s[98:99]
	v_lshl_add_u64 v[246:247], v[86:87], 0, s[98:99]
	v_mfma_f32_16x16x32_bf16 v[2:5], v[122:125], v[130:133], v[2:5]
	v_lshl_add_u32 v109, v104, 1, s7
	v_add3_u32 v251, v109, v105, v106
	v_add3_u32 v109, v109, v107, v106
	s_cmp_eq_u32 s6, 16
	s_cbranch_scc0 .LBB0_176
	s_setprio 0
	s_waitcnt vmcnt(0)
	v_add_u32_e32 v78, s0, v0
	v_or_b32_e32 v82, s1, v75
	s_waitcnt lgkmcnt(0)
	s_barrier
	v_ashrrev_i32_e32 v83, 31, v82
	v_ashrrev_i32_e32 v79, 31, v78
	v_lshl_add_u64 v[76:77], v[82:83], 1, s[76:77]
	v_lshlrev_b64 v[80:81], 11, v[78:79]
	s_movk_i32 s0, 0x400
	v_lshl_add_u64 v[80:81], v[76:77], 0, v[80:81]
	v_cmp_gt_i32_e32 vcc, s0, v82
	s_and_saveexec_b64 s[0:1], vcc
	s_cbranch_execz .LBB0_179
	v_bfe_u32 v79, v64, 16, 1
	v_add3_u32 v64, v64, v79, s96
	global_store_short_d16_hi v[80:81], v64, off

; template <int EPI>
; __device__ void gemm_phase(const u16* __restrict__ A, const u16* __restrict__ Bt, void* __restrict__ Cv,
;                            int N, int K, int ldc, unsigned char* ldsraw, int G) {
;     ...
;     f32x4 acc[4][4];
; #pragma unroll
;     for (int i = 0; i < 4; ++i)
; #pragma unroll
;       for (int j = 0; j < 4; ++j) acc[i][j] = (f32x4){0.f, 0.f, 0.f, 0.f};
;     const int ar0 = tid >> 3, acc4 = tid & 7;
;     const int ssw = (acc4 ^ ((ar0 >> 1) & 7)) * 8;
;     const int fx = (l15 >> 1) & 7;
;     const u16* Ag0 = A + (size_t)(m0 + ar0) * K + ssw;
;     const u16* Bg = Bt + (size_t)(n0 + ar0) * K + ssw;
;     const size_t r64 = (size_t)64 * K;
;     constexpr int STG = (GBM + GBN) * GLD;
;     const unsigned lw0 = (unsigned)__builtin_amdgcn_readfirstlane((int)(unsigned)(uintptr_t)(As + wave * 8 * GLD));
;     ...
;     GLDS(0, 0);
;     GLDS(1, 1);
.LBB0_829:
	v_mov_b32_e32 v2, 0
	s_mov_b32 s4, 0
	s_mov_b32 s5, 0
	v_mov_b32_e32 v3, v2
	v_mov_b32_e32 v4, v2
	v_mov_b32_e32 v5, v2
	v_mov_b32_e32 v8, v2
	v_mov_b32_e32 v9, v2
	v_mov_b32_e32 v10, v2
	v_mov_b32_e32 v11, v2
	v_mov_b32_e32 v12, v2
	v_mov_b32_e32 v13, v2
	v_mov_b32_e32 v14, v2
	v_mov_b32_e32 v15, v2
	v_mov_b32_e32 v16, v2
	v_mov_b32_e32 v17, v2
	v_mov_b32_e32 v18, v2
	v_mov_b32_e32 v19, v2
	v_mov_b32_e32 v20, v2
	v_mov_b32_e32 v21, v2
	v_mov_b32_e32 v22, v2
	v_mov_b32_e32 v23, v2
	v_mov_b32_e32 v24, v2
	v_mov_b32_e32 v25, v2
	v_mov_b32_e32 v26, v2
	v_mov_b32_e32 v27, v2
	v_mov_b32_e32 v28, v2
	v_mov_b32_e32 v29, v2
	v_mov_b32_e32 v30, v2
	v_mov_b32_e32 v31, v2
	v_mov_b32_e32 v32, v2
	v_mov_b32_e32 v33, v2
	v_mov_b32_e32 v34, v2
	v_mov_b32_e32 v35, v2
	v_mov_b32_e32 v36, v2
	v_mov_b32_e32 v37, v2
	v_mov_b32_e32 v38, v2
	v_mov_b32_e32 v39, v2
	v_mov_b32_e32 v40, v2
	v_mov_b32_e32 v41, v2
	v_mov_b32_e32 v42, v2
	v_mov_b32_e32 v43, v2
	v_mov_b32_e32 v44, v2
	v_mov_b32_e32 v45, v2
	v_mov_b32_e32 v46, v2
	v_mov_b32_e32 v47, v2
	v_mov_b32_e32 v48, v2
	v_mov_b32_e32 v49, v2
	v_mov_b32_e32 v50, v2
	v_mov_b32_e32 v51, v2
	v_mov_b32_e32 v52, v2
	v_mov_b32_e32 v53, v2
	v_mov_b32_e32 v54, v2
	v_mov_b32_e32 v55, v2
	v_mov_b32_e32 v56, v2
	v_mov_b32_e32 v57, v2
	v_mov_b32_e32 v58, v2
	v_mov_b32_e32 v59, v2
	v_mov_b32_e32 v60, v2
	v_mov_b32_e32 v61, v2
	v_mov_b32_e32 v62, v2
	v_mov_b32_e32 v63, v2
	v_mov_b32_e32 v64, v2
	v_mov_b32_e32 v65, v2
	v_mov_b32_e32 v66, v2
	v_mov_b32_e32 v67, v2
	s_mul_i32 s7, s4, 0xc000
	s_min_u32 s6, s5, 13
	s_add_i32 s8, s7, 0xffff4000
	s_cmp_gt_i32 s4, 0
	s_cselect_b32 s8, s8, 0x18000
	s_lshl_b32 s98, s6, 7
	s_add_i32 s98, s98, 0x100
	s_add_i32 s6, s7, 0x100
	s_add_i32 s7, s8, s3
	s_add_i32 s8, s7, 0x2000
	s_add_i32 s9, s7, 0x4000
	s_add_i32 s10, s7, 0x6000
	s_add_i32 s11, s7, 0x8000
	s_add_i32 s12, s7, 0xa000
	v_lshl_add_u64 v[236:237], v[76:77], 0, s[98:99]
	v_lshl_add_u64 v[238:239], v[80:81], 0, s[98:99]
	v_lshl_add_u64 v[240:241], v[82:83], 0, s[98:99]
	v_lshl_add_u64 v[242:243], v[84:85], 0, s[98:99]
	v_lshl_add_u64 v[244:245], v[78:79], 0, s[98:99]
	v_lshl_add_u64 v[246:247], v[86:87], 0, s[98:99]
	v_lshl_add_u32 v109, v104, 1, s6
	v_add3_u32 v251, v109, v105, v106
	v_add3_u32 v109, v109, v107, v106
; __device__ __forceinline__ void lds_barrier() { asm volatile("s_waitcnt lgkmcnt(0)\n\ts_barrier" ::: "memory"); }
; template <int EPI>
; __device__ void gemm_phase(const u16* __restrict__ A, const u16* __restrict__ Bt, void* __restrict__ Cv,
;                            int N, int K, int ldc, unsigned char* ldsraw, int G) {
;     ...
;     for (int kt = 0; kt < nk; ++kt) {
;       asm volatile("s_waitcnt vmcnt(6)" ::: "memory");
;       lds_barrier();
;       const int st2 = (st >= 1) ? st - 1 : 2;
;       GLDS(st2, kt + 2);
;       const u16* Asx = As + st * STG;
;       const u16* Bsx = Asx + GBM * GLD;
; #pragma unroll
;       for (int ks = 0; ks < 2; ++ks) {
;         const int fsw = ((ks * 4 + g4) ^ fx) * 8;
;         bf16x8 bfr[4];
; #pragma unroll
;         for (int jx = 0; jx < 4; ++jx) bfr[jx] = *(const bf16x8*)(Bsx + (wn * 64 + jx * 16 + l15) * GLD + fsw);
; #pragma unroll
;         for (int ix = 0; ix < 4; ++ix) {
;           const bf16x8 af = *(const bf16x8*)(Asx + (wm * 64 + ix * 16 + l15) * GLD + fsw);
; #pragma unroll
;           for (int jx = 0; jx < 4; ++jx)
;             acc[ix][jx] = __builtin_amdgcn_mfma_f32_16x16x32_bf16(af, bfr[jx], acc[ix][jx], 0, 0, 0);
;         }
;       }
;       st = (st == 2) ? 0 : st + 1;
;     }
;     __builtin_amdgcn_s_setprio(0);
;     asm volatile("s_waitcnt vmcnt(0)" ::: "memory");
;     lds_barrier();
;     ...
; #pragma unroll
;     for (int i = 0; i < 4; ++i) {
; #pragma unroll
;       for (int r = 0; r < 4; ++r) {
;         const int m = m0 + wm * 64 + i * 16 + g4 * 4 + r;
;         const int nb = n0 + wn * 64 + l15;
;         if (EPI == EPI_F32) {
;           float* cp = (float*)Cv + (size_t)m * ldc + nb;
; #pragma unroll
;           for (int j = 0; j < 4; ++j) if (nb + j * 16 < N) cp[j * 16] = acc[i][j][r];
;         } else {
;           u16* cp = (u16*)Cv + (size_t)m * ldc + nb;
; #pragma unroll
;           for (int j = 0; j < 4; ++j) {
;             float v = acc[i][j][r];
;             if (EPI == EPI_RELU2) { v = fmaxf(v, 0.f); v = v * v; }
;             if (nb + j * 16 < N) cp[j * 16] = f2bf(v);
.LBB0_830:
	s_waitcnt vmcnt(6)
	s_waitcnt lgkmcnt(0)
	s_barrier
	s_mov_b32 s13, m0
	ds_read_b128 v[110:113], v109
	ds_read_b128 v[114:117], v251 offset:32768
	ds_read_b128 v[118:121], v251 offset:34816
	ds_read_b128 v[122:125], v109 offset:2048
	ds_read_b128 v[126:129], v251 offset:36864
	ds_read_b128 v[130:133], v251 offset:38912
	s_waitcnt lgkmcnt(4)
	v_mfma_f32_16x16x32_bf16 v[64:67], v[110:113], v[114:117], v[64:67]
	s_waitcnt lgkmcnt(3)
	v_mfma_f32_16x16x32_bf16 v[60:63], v[110:113], v[118:121], v[60:63]
	s_waitcnt lgkmcnt(1)
	v_mfma_f32_16x16x32_bf16 v[56:59], v[110:113], v[126:129], v[56:59]
	s_waitcnt lgkmcnt(0)
	s_mov_b32 m0, s7
	v_mfma_f32_16x16x32_bf16 v[52:55], v[110:113], v[130:133], v[52:55]
	global_load_lds_dwordx4 v[236:237], off
	v_mfma_f32_16x16x32_bf16 v[48:51], v[122:125], v[114:117], v[48:51]
	v_mfma_f32_16x16x32_bf16 v[44:47], v[122:125], v[118:121], v[44:47]
	v_mfma_f32_16x16x32_bf16 v[40:43], v[122:125], v[126:129], v[40:43]
	v_mfma_f32_16x16x32_bf16 v[36:39], v[122:125], v[130:133], v[36:39]
	ds_read_b128 v[110:113], v109 offset:4096
	ds_read_b128 v[122:125], v109 offset:6144
	v_lshl_add_u32 v109, v108, 1, s6
	v_add3_u32 v134, v109, v105, v106
	v_add3_u32 v109, v109, v107, v106
	s_waitcnt lgkmcnt(1)
	s_mov_b32 m0, s8
	v_mfma_f32_16x16x32_bf16 v[32:35], v[110:113], v[114:117], v[32:35]
	global_load_lds_dwordx4 v[238:239], off
	s_add_i32 s6, s4, 1
	s_cmp_lg_u32 s4, 2
	s_cselect_b32 s4, s6, 0
	v_mfma_f32_16x16x32_bf16 v[28:31], v[110:113], v[118:121], v[28:31]
	s_add_i32 s5, s5, 1
	v_mfma_f32_16x16x32_bf16 v[24:27], v[110:113], v[126:129], v[24:27]
	v_mfma_f32_16x16x32_bf16 v[20:23], v[110:113], v[130:133], v[20:23]
	ds_read_b128 v[110:113], v109
	s_waitcnt lgkmcnt(1)
	v_mfma_f32_16x16x32_bf16 v[16:19], v[122:125], v[114:117], v[16:19]
	s_mov_b32 m0, s9
	v_mfma_f32_16x16x32_bf16 v[12:15], v[122:125], v[118:121], v[12:15]
	global_load_lds_dwordx4 v[240:241], off
	v_mfma_f32_16x16x32_bf16 v[8:11], v[122:125], v[126:129], v[8:11]
	v_mfma_f32_16x16x32_bf16 v[2:5], v[122:125], v[130:133], v[2:5]
	ds_read_b128 v[114:117], v134 offset:32768
	ds_read_b128 v[118:121], v134 offset:34816
	ds_read_b128 v[122:125], v109 offset:2048
	ds_read_b128 v[126:129], v134 offset:36864
	ds_read_b128 v[130:133], v134 offset:38912
	s_waitcnt lgkmcnt(4)
	v_mfma_f32_16x16x32_bf16 v[64:67], v[110:113], v[114:117], v[64:67]
	s_waitcnt lgkmcnt(3)
	v_mfma_f32_16x16x32_bf16 v[60:63], v[110:113], v[118:121], v[60:63]
	s_waitcnt lgkmcnt(1)
	s_mov_b32 m0, s10
	v_mfma_f32_16x16x32_bf16 v[56:59], v[110:113], v[126:129], v[56:59]
	global_load_lds_dwordx4 v[242:243], off
	s_waitcnt lgkmcnt(0)
	v_mfma_f32_16x16x32_bf16 v[52:55], v[110:113], v[130:133], v[52:55]
	v_mfma_f32_16x16x32_bf16 v[48:51], v[122:125], v[114:117], v[48:51]
	v_mfma_f32_16x16x32_bf16 v[44:47], v[122:125], v[118:121], v[44:47]
	v_mfma_f32_16x16x32_bf16 v[40:43], v[122:125], v[126:129], v[40:43]
	s_mov_b32 m0, s11
	v_mfma_f32_16x16x32_bf16 v[36:39], v[122:125], v[130:133], v[36:39]
	global_load_lds_dwordx4 v[244:245], off
	ds_read_b128 v[110:113], v109 offset:4096
	ds_read_b128 v[122:125], v109 offset:6144
	s_waitcnt lgkmcnt(1)
	v_mfma_f32_16x16x32_bf16 v[32:35], v[110:113], v[114:117], v[32:35]
	v_mfma_f32_16x16x32_bf16 v[28:31], v[110:113], v[118:121], v[28:31]
	v_mfma_f32_16x16x32_bf16 v[24:27], v[110:113], v[126:129], v[24:27]
	v_mfma_f32_16x16x32_bf16 v[20:23], v[110:113], v[130:133], v[20:23]
	s_waitcnt lgkmcnt(0)
	s_mov_b32 m0, s12
	v_mfma_f32_16x16x32_bf16 v[16:19], v[122:125], v[114:117], v[16:19]
	global_load_lds_dwordx4 v[246:247], off
	s_mov_b32 m0, s13
	s_mul_i32 s7, s4, 0xc000
	s_min_u32 s6, s5, 13
	s_add_i32 s8, s7, 0xffff4000
	s_cmp_gt_i32 s4, 0
	s_cselect_b32 s8, s8, 0x18000
	s_lshl_b32 s98, s6, 7
	s_add_i32 s98, s98, 0x100
	s_add_i32 s6, s7, 0x100
	s_add_i32 s7, s8, s3
	s_add_i32 s8, s7, 0x2000
	s_add_i32 s9, s7, 0x4000
	s_add_i32 s10, s7, 0x6000
	s_add_i32 s11, s7, 0x8000
	s_add_i32 s12, s7, 0xa000
	v_mfma_f32_16x16x32_bf16 v[12:15], v[122:125], v[118:121], v[12:15]
	v_lshl_add_u64 v[236:237], v[76:77], 0, s[98:99]
	v_lshl_add_u64 v[238:239], v[80:81], 0, s[98:99]
	v_lshl_add_u64 v[240:241], v[82:83], 0, s[98:99]
	v_mfma_f32_16x16x32_bf16 v[8:11], v[122:125], v[126:129], v[8:11]
	v_lshl_add_u64 v[242:243], v[84:85], 0, s[98:99]
	v_lshl_add_u64 v[244:245], v[78:79], 0, s[98:99]
	v_lshl_add_u64 v[246:247], v[86:87], 0, s[98:99]
	v_mfma_f32_16x16x32_bf16 v[2:5], v[122:125], v[130:133], v[2:5]
	v_lshl_add_u32 v109, v104, 1, s6
	v_add3_u32 v251, v109, v105, v106
	v_add3_u32 v109, v109, v107, v106
	s_cmp_eq_u32 s5, 16
	s_cbranch_scc0 .LBB0_830
	s_setprio 0
	v_or_b32_e32 v80, s1, v75
	v_ashrrev_i32_e32 v81, 31, v80
	s_waitcnt vmcnt(0)
	v_add_u32_e32 v82, s0, v0
	v_lshl_add_u64 v[76:77], v[80:81], 1, s[76:77]
	s_waitcnt lgkmcnt(0)
	s_barrier
	v_mad_i64_i32 v[78:79], s[0:1], v82, s83, v[76:77]
	s_movk_i32 s0, 0xc90
	s_nop 0
	v_cmp_gt_i32_e32 vcc, s0, v80
	s_and_saveexec_b64 s[0:1], vcc
	s_cbranch_execz .LBB0_833
	v_bfe_u32 v81, v64, 16, 1
	v_add3_u32 v64, v64, v81, s96
	global_store_short_d16_hi v[78:79], v64, off
